# GEMM loop: load segments at high priority + scalar address arithmetic moved into MFMA segments
# baseline (speedup 1.0000x reference)
.LBB0_176:
	s_mov_b32 m0, s55
	s_nop 0
	global_load_lds_dwordx4 v194, s[100:101]
	s_mov_b32 m0, s67
	s_nop 0
	global_load_lds_dwordx4 v196, s[100:101]
	v_add_u32_e32 v130, 0x10000, v243
	v_add_u32_e32 v142, 0x14000, v243
	ds_read_b128 v[146:149], v130
	ds_read_b128 v[150:153], v130 offset:1024
	ds_read_b128 v[154:157], v130 offset:2048
	ds_read_b128 v[158:161], v130 offset:3072
	ds_read_b128 v[130:133], v142
	ds_read_b128 v[134:137], v142 offset:1024
	ds_read_b128 v[138:141], v142 offset:2048
	ds_read_b128 v[142:145], v142 offset:3072
	v_lshl_add_u64 v[246:247], v[234:235], 0, s[80:81]
	s_add_i32 m0, s8, 0xc000
	s_waitcnt lgkmcnt(0)
	ds_read_b128 v[174:177], v244
	ds_read_b128 v[190:193], v244 offset:1024
	ds_read_b128 v[170:173], v244 offset:2048
	ds_read_b128 v[186:189], v244 offset:3072
	ds_read_b128 v[166:169], v244 offset:4096
	ds_read_b128 v[182:185], v244 offset:5120
	ds_read_b128 v[162:165], v244 offset:6144
	ds_read_b128 v[178:181], v244 offset:7168
	global_load_lds_dwordx4 v[246:247], off
	v_lshl_add_u64 v[246:247], v[236:237], 0, s[80:81]
	s_add_i32 m0, s8, 0xe000
	s_nop 0
	global_load_lds_dwordx4 v[246:247], off
	s_waitcnt vmcnt(8)
	s_waitcnt lgkmcnt(0)
	s_barrier
	s_setprio 0
	s_waitcnt lgkmcnt(0)
	v_mfma_f32_16x16x32_bf16 v[118:121], v[146:149], v[174:177], v[118:121]
	v_mfma_f32_16x16x32_bf16 v[126:129], v[154:157], v[174:177], v[126:129]
	v_mfma_f32_16x16x32_bf16 v[102:105], v[146:149], v[170:173], v[102:105]
	v_mfma_f32_16x16x32_bf16 v[110:113], v[154:157], v[170:173], v[110:113]
	v_mfma_f32_16x16x32_bf16 v[86:89], v[146:149], v[166:169], v[86:89]
	v_mfma_f32_16x16x32_bf16 v[94:97], v[154:157], v[166:169], v[94:97]
	v_mfma_f32_16x16x32_bf16 v[70:73], v[146:149], v[162:165], v[70:73]
	v_mfma_f32_16x16x32_bf16 v[78:81], v[154:157], v[162:165], v[78:81]
	v_mfma_f32_16x16x32_bf16 v[118:121], v[150:153], v[190:193], v[118:121]
	v_mfma_f32_16x16x32_bf16 v[126:129], v[158:161], v[190:193], v[126:129]
	v_mfma_f32_16x16x32_bf16 v[102:105], v[150:153], v[186:189], v[102:105]
	v_mfma_f32_16x16x32_bf16 v[110:113], v[158:161], v[186:189], v[110:113]
	v_mfma_f32_16x16x32_bf16 v[86:89], v[150:153], v[182:185], v[86:89]
	v_mfma_f32_16x16x32_bf16 v[94:97], v[158:161], v[182:185], v[94:97]
	v_mfma_f32_16x16x32_bf16 v[70:73], v[150:153], v[178:181], v[70:73]
	v_mfma_f32_16x16x32_bf16 v[78:81], v[158:161], v[178:181], v[78:81]
	s_setprio 1
	s_setprio 0
	v_mfma_f32_16x16x32_bf16 v[122:125], v[130:133], v[174:177], v[122:125]
	v_mfma_f32_16x16x32_bf16 v[114:117], v[138:141], v[174:177], v[114:117]
	v_mfma_f32_16x16x32_bf16 v[106:109], v[130:133], v[170:173], v[106:109]
	v_mfma_f32_16x16x32_bf16 v[98:101], v[138:141], v[170:173], v[98:101]
	v_mfma_f32_16x16x32_bf16 v[90:93], v[130:133], v[166:169], v[90:93]
	v_mfma_f32_16x16x32_bf16 v[82:85], v[138:141], v[166:169], v[82:85]
	v_mfma_f32_16x16x32_bf16 v[74:77], v[130:133], v[162:165], v[74:77]
	v_mfma_f32_16x16x32_bf16 v[66:69], v[138:141], v[162:165], v[66:69]
	v_mfma_f32_16x16x32_bf16 v[122:125], v[134:137], v[190:193], v[122:125]
	v_mfma_f32_16x16x32_bf16 v[114:117], v[142:145], v[190:193], v[114:117]
	v_mfma_f32_16x16x32_bf16 v[106:109], v[134:137], v[186:189], v[106:109]
	v_mfma_f32_16x16x32_bf16 v[98:101], v[142:145], v[186:189], v[98:101]
	s_barrier
	v_mfma_f32_16x16x32_bf16 v[90:93], v[134:137], v[182:185], v[90:93]
	v_mfma_f32_16x16x32_bf16 v[82:85], v[142:145], v[182:185], v[82:85]
	v_mfma_f32_16x16x32_bf16 v[74:77], v[134:137], v[178:181], v[74:77]
	v_mfma_f32_16x16x32_bf16 v[66:69], v[142:145], v[178:181], v[66:69]
	s_setprio 1
	v_cndmask_b32_e64 v246, 0, 1, s[50:51]
	v_cmp_ne_u32_e64 s[48:49], 1, v246
	s_andn2_b64 vcc, exec, s[50:51]
	s_cbranch_vccnz .LBB0_178
	ds_read_b128 v[174:177], v244 offset:16384
	ds_read_b128 v[190:193], v244 offset:17408
	ds_read_b128 v[170:173], v244 offset:18432
	ds_read_b128 v[186:189], v244 offset:19456
	ds_read_b128 v[166:169], v244 offset:20480
	ds_read_b128 v[182:185], v244 offset:21504
	ds_read_b128 v[162:165], v244 offset:22528
	ds_read_b128 v[178:181], v244 offset:23552

.LBB0_180:
	s_and_b64 vcc, s[46:47], s[86:87]
	v_cndmask_b32_e64 v131, v233, 0, vcc
	v_cndmask_b32_e32 v130, v232, v198, vcc
	v_lshl_add_u64 v[246:247], s[84:85], 0, v[130:131]
	s_barrier
	s_mov_b32 m0, s8
	s_nop 0
	global_load_lds_dwordx4 v194, s[98:99]
	s_mov_b32 m0, s13
	s_nop 0
	global_load_lds_dwordx4 v196, s[98:99]
	v_add_u32_e32 v130, 0x18000, v243
	v_add_u32_e32 v142, 0x1c000, v243
	ds_read_b128 v[146:149], v130
	ds_read_b128 v[150:153], v130 offset:1024
	ds_read_b128 v[154:157], v130 offset:2048
	ds_read_b128 v[158:161], v130 offset:3072
	ds_read_b128 v[130:133], v142
	ds_read_b128 v[134:137], v142 offset:1024
	ds_read_b128 v[138:141], v142 offset:2048
	ds_read_b128 v[142:145], v142 offset:3072
	s_mov_b32 m0, s14
	v_lshl_add_u64 v[248:249], v[246:247], 0, v[194:195]
	s_waitcnt lgkmcnt(0)
	ds_read_b128 v[174:177], v244 offset:32768
	ds_read_b128 v[190:193], v244 offset:33792
	ds_read_b128 v[170:173], v244 offset:34816
	ds_read_b128 v[186:189], v244 offset:35840
	ds_read_b128 v[166:169], v244 offset:36864
	ds_read_b128 v[182:185], v244 offset:37888
	ds_read_b128 v[162:165], v244 offset:38912
	ds_read_b128 v[178:181], v244 offset:39936
	global_load_lds_dwordx4 v[248:249], off
	v_lshl_add_u64 v[246:247], v[246:247], 0, v[196:197]
	s_mov_b32 m0, s15
	s_nop 0
	global_load_lds_dwordx4 v[246:247], off
	s_waitcnt vmcnt(8)
	s_waitcnt lgkmcnt(0)
	s_barrier
	s_setprio 0
	s_waitcnt lgkmcnt(0)
	v_mfma_f32_16x16x32_bf16 v[118:121], v[146:149], v[174:177], v[118:121]
	v_mfma_f32_16x16x32_bf16 v[126:129], v[154:157], v[174:177], v[126:129]
	v_mfma_f32_16x16x32_bf16 v[102:105], v[146:149], v[170:173], v[102:105]
	v_mfma_f32_16x16x32_bf16 v[110:113], v[154:157], v[170:173], v[110:113]
	v_mfma_f32_16x16x32_bf16 v[86:89], v[146:149], v[166:169], v[86:89]
	v_mfma_f32_16x16x32_bf16 v[94:97], v[154:157], v[166:169], v[94:97]
	v_mfma_f32_16x16x32_bf16 v[70:73], v[146:149], v[162:165], v[70:73]
	v_mfma_f32_16x16x32_bf16 v[78:81], v[154:157], v[162:165], v[78:81]
	v_mfma_f32_16x16x32_bf16 v[118:121], v[150:153], v[190:193], v[118:121]
	v_mfma_f32_16x16x32_bf16 v[126:129], v[158:161], v[190:193], v[126:129]
	v_mfma_f32_16x16x32_bf16 v[102:105], v[150:153], v[186:189], v[102:105]
	v_mfma_f32_16x16x32_bf16 v[110:113], v[158:161], v[186:189], v[110:113]
	v_mfma_f32_16x16x32_bf16 v[86:89], v[150:153], v[182:185], v[86:89]
	v_mfma_f32_16x16x32_bf16 v[94:97], v[158:161], v[182:185], v[94:97]
	v_mfma_f32_16x16x32_bf16 v[70:73], v[150:153], v[178:181], v[70:73]
	v_mfma_f32_16x16x32_bf16 v[78:81], v[158:161], v[178:181], v[78:81]
	s_setprio 1
	s_setprio 0
	v_mfma_f32_16x16x32_bf16 v[122:125], v[130:133], v[174:177], v[122:125]
	v_mfma_f32_16x16x32_bf16 v[114:117], v[138:141], v[174:177], v[114:117]
	v_mfma_f32_16x16x32_bf16 v[106:109], v[130:133], v[170:173], v[106:109]
	v_mfma_f32_16x16x32_bf16 v[98:101], v[138:141], v[170:173], v[98:101]
	v_mfma_f32_16x16x32_bf16 v[90:93], v[130:133], v[166:169], v[90:93]
	v_mfma_f32_16x16x32_bf16 v[82:85], v[138:141], v[166:169], v[82:85]
	v_mfma_f32_16x16x32_bf16 v[74:77], v[130:133], v[162:165], v[74:77]
	v_mfma_f32_16x16x32_bf16 v[66:69], v[138:141], v[162:165], v[66:69]
	v_mfma_f32_16x16x32_bf16 v[122:125], v[134:137], v[190:193], v[122:125]
	v_mfma_f32_16x16x32_bf16 v[114:117], v[142:145], v[190:193], v[114:117]
	v_mfma_f32_16x16x32_bf16 v[106:109], v[134:137], v[186:189], v[106:109]
	v_mfma_f32_16x16x32_bf16 v[98:101], v[142:145], v[186:189], v[98:101]
	s_barrier
	v_mfma_f32_16x16x32_bf16 v[90:93], v[134:137], v[182:185], v[90:93]
	v_mfma_f32_16x16x32_bf16 v[82:85], v[142:145], v[182:185], v[82:85]
	v_mfma_f32_16x16x32_bf16 v[74:77], v[134:137], v[178:181], v[74:77]
	v_mfma_f32_16x16x32_bf16 v[66:69], v[142:145], v[178:181], v[66:69]
	s_setprio 1
	s_and_b64 vcc, exec, s[48:49]
	s_cbranch_vccnz .LBB0_182
	ds_read_b128 v[174:177], v244 offset:49152
	ds_read_b128 v[190:193], v244 offset:50176
	ds_read_b128 v[170:173], v244 offset:51200
	ds_read_b128 v[186:189], v244 offset:52224
	ds_read_b128 v[166:169], v244 offset:53248
	ds_read_b128 v[182:185], v244 offset:54272
	ds_read_b128 v[162:165], v244 offset:55296
	ds_read_b128 v[178:181], v244 offset:56320

.LBB0_559:
	s_mov_b32 m0, s55
	s_nop 0
	global_load_lds_dwordx4 v194, s[100:101]
	s_mov_b32 m0, s67
	s_nop 0
	global_load_lds_dwordx4 v196, s[100:101]
	ds_read_b128 v[146:149], v227
	ds_read_b128 v[150:153], v227 offset:1024
	ds_read_b128 v[154:157], v227 offset:2048
	ds_read_b128 v[158:161], v227 offset:3072
	ds_read_b128 v[130:133], v228
	ds_read_b128 v[134:137], v228 offset:1024
	ds_read_b128 v[138:141], v228 offset:2048
	ds_read_b128 v[142:145], v228 offset:3072
	v_lshl_add_u64 v[234:235], v[216:217], 0, s[58:59]
	s_add_i32 m0, s8, 0xc000
	s_waitcnt lgkmcnt(0)
	ds_read_b128 v[174:177], v229
	ds_read_b128 v[190:193], v229 offset:1024
	ds_read_b128 v[170:173], v229 offset:2048
	ds_read_b128 v[186:189], v229 offset:3072
	ds_read_b128 v[166:169], v229 offset:4096
	ds_read_b128 v[182:185], v229 offset:5120
	ds_read_b128 v[162:165], v229 offset:6144
	ds_read_b128 v[178:181], v229 offset:7168
	global_load_lds_dwordx4 v[234:235], off
	v_lshl_add_u64 v[234:235], v[218:219], 0, s[58:59]
	s_add_i32 m0, s8, 0xe000
	s_nop 0
	global_load_lds_dwordx4 v[234:235], off
	s_waitcnt vmcnt(8)
	s_waitcnt lgkmcnt(0)
	s_barrier
	s_setprio 0
	s_waitcnt lgkmcnt(0)
	v_mfma_f32_16x16x32_bf16 v[126:129], v[146:149], v[174:177], v[126:129]
	v_mfma_f32_16x16x32_bf16 v[122:125], v[154:157], v[174:177], v[122:125]
	v_mfma_f32_16x16x32_bf16 v[110:113], v[146:149], v[170:173], v[110:113]
	v_mfma_f32_16x16x32_bf16 v[106:109], v[154:157], v[170:173], v[106:109]
	v_mfma_f32_16x16x32_bf16 v[94:97], v[146:149], v[166:169], v[94:97]
	v_mfma_f32_16x16x32_bf16 v[90:93], v[154:157], v[166:169], v[90:93]
	v_mfma_f32_16x16x32_bf16 v[78:81], v[146:149], v[162:165], v[78:81]
	v_mfma_f32_16x16x32_bf16 v[74:77], v[154:157], v[162:165], v[74:77]
	v_mfma_f32_16x16x32_bf16 v[126:129], v[150:153], v[190:193], v[126:129]
	v_mfma_f32_16x16x32_bf16 v[122:125], v[158:161], v[190:193], v[122:125]
	v_mfma_f32_16x16x32_bf16 v[110:113], v[150:153], v[186:189], v[110:113]
	v_mfma_f32_16x16x32_bf16 v[106:109], v[158:161], v[186:189], v[106:109]
	v_mfma_f32_16x16x32_bf16 v[94:97], v[150:153], v[182:185], v[94:97]
	v_mfma_f32_16x16x32_bf16 v[90:93], v[158:161], v[182:185], v[90:93]
	v_mfma_f32_16x16x32_bf16 v[78:81], v[150:153], v[178:181], v[78:81]
	v_mfma_f32_16x16x32_bf16 v[74:77], v[158:161], v[178:181], v[74:77]
	s_setprio 1
	s_setprio 0
	v_mfma_f32_16x16x32_bf16 v[118:121], v[130:133], v[174:177], v[118:121]
	v_mfma_f32_16x16x32_bf16 v[114:117], v[138:141], v[174:177], v[114:117]
	v_mfma_f32_16x16x32_bf16 v[102:105], v[130:133], v[170:173], v[102:105]
	v_mfma_f32_16x16x32_bf16 v[98:101], v[138:141], v[170:173], v[98:101]
	v_mfma_f32_16x16x32_bf16 v[86:89], v[130:133], v[166:169], v[86:89]
	v_mfma_f32_16x16x32_bf16 v[82:85], v[138:141], v[166:169], v[82:85]
	v_mfma_f32_16x16x32_bf16 v[70:73], v[130:133], v[162:165], v[70:73]
	v_mfma_f32_16x16x32_bf16 v[66:69], v[138:141], v[162:165], v[66:69]
	v_mfma_f32_16x16x32_bf16 v[118:121], v[134:137], v[190:193], v[118:121]
	v_mfma_f32_16x16x32_bf16 v[114:117], v[142:145], v[190:193], v[114:117]
	v_mfma_f32_16x16x32_bf16 v[102:105], v[134:137], v[186:189], v[102:105]
	v_mfma_f32_16x16x32_bf16 v[98:101], v[142:145], v[186:189], v[98:101]
	s_barrier
	v_mfma_f32_16x16x32_bf16 v[86:89], v[134:137], v[182:185], v[86:89]
	v_mfma_f32_16x16x32_bf16 v[82:85], v[142:145], v[182:185], v[82:85]
	v_mfma_f32_16x16x32_bf16 v[70:73], v[134:137], v[178:181], v[70:73]
	v_mfma_f32_16x16x32_bf16 v[66:69], v[142:145], v[178:181], v[66:69]
	s_setprio 1
	v_cmp_ne_u32_e64 s[42:43], 1, v233
	s_andn2_b64 vcc, exec, s[44:45]
	s_cbranch_vccnz .LBB0_561
	ds_read_b128 v[174:177], v229 offset:16384
	ds_read_b128 v[190:193], v229 offset:17408
	ds_read_b128 v[170:173], v229 offset:18432
	ds_read_b128 v[186:189], v229 offset:19456
	ds_read_b128 v[166:169], v229 offset:20480
	ds_read_b128 v[182:185], v229 offset:21504
	ds_read_b128 v[162:165], v229 offset:22528
	ds_read_b128 v[178:181], v229 offset:23552

.LBB0_563:
	s_and_b64 vcc, s[40:41], s[68:69]
	v_cndmask_b32_e64 v131, v215, 0, vcc
	v_cndmask_b32_e32 v130, v214, v198, vcc
	v_lshl_add_u64 v[234:235], s[62:63], 0, v[130:131]
	s_barrier
	s_mov_b32 m0, s8
	s_nop 0
	global_load_lds_dwordx4 v194, s[98:99]
	s_mov_b32 m0, s13
	s_nop 0
	global_load_lds_dwordx4 v196, s[98:99]
	v_add_u32_e32 v130, 0x18000, v226
	v_add_u32_e32 v142, 0x1c000, v226
	ds_read_b128 v[146:149], v130
	ds_read_b128 v[150:153], v130 offset:1024
	ds_read_b128 v[154:157], v130 offset:2048
	ds_read_b128 v[158:161], v130 offset:3072
	ds_read_b128 v[130:133], v142
	ds_read_b128 v[134:137], v142 offset:1024
	ds_read_b128 v[138:141], v142 offset:2048
	ds_read_b128 v[142:145], v142 offset:3072
	s_mov_b32 m0, s14
	v_lshl_add_u64 v[236:237], v[234:235], 0, v[194:195]
	s_waitcnt lgkmcnt(0)
	ds_read_b128 v[174:177], v229 offset:32768
	ds_read_b128 v[190:193], v229 offset:33792
	ds_read_b128 v[170:173], v229 offset:34816
	ds_read_b128 v[186:189], v229 offset:35840
	ds_read_b128 v[166:169], v229 offset:36864
	ds_read_b128 v[182:185], v229 offset:37888
	ds_read_b128 v[162:165], v229 offset:38912
	ds_read_b128 v[178:181], v229 offset:39936
	global_load_lds_dwordx4 v[236:237], off
	v_lshl_add_u64 v[234:235], v[234:235], 0, v[196:197]
	s_mov_b32 m0, s15
	s_nop 0
	global_load_lds_dwordx4 v[234:235], off
	s_waitcnt vmcnt(8)
	s_waitcnt lgkmcnt(0)
	s_barrier
	s_setprio 0
	s_waitcnt lgkmcnt(0)
	v_mfma_f32_16x16x32_bf16 v[126:129], v[146:149], v[174:177], v[126:129]
	v_mfma_f32_16x16x32_bf16 v[122:125], v[154:157], v[174:177], v[122:125]
	v_mfma_f32_16x16x32_bf16 v[110:113], v[146:149], v[170:173], v[110:113]
	v_mfma_f32_16x16x32_bf16 v[106:109], v[154:157], v[170:173], v[106:109]
	v_mfma_f32_16x16x32_bf16 v[94:97], v[146:149], v[166:169], v[94:97]
	v_mfma_f32_16x16x32_bf16 v[90:93], v[154:157], v[166:169], v[90:93]
	v_mfma_f32_16x16x32_bf16 v[78:81], v[146:149], v[162:165], v[78:81]
	v_mfma_f32_16x16x32_bf16 v[74:77], v[154:157], v[162:165], v[74:77]
	v_mfma_f32_16x16x32_bf16 v[126:129], v[150:153], v[190:193], v[126:129]
	v_mfma_f32_16x16x32_bf16 v[122:125], v[158:161], v[190:193], v[122:125]
	v_mfma_f32_16x16x32_bf16 v[110:113], v[150:153], v[186:189], v[110:113]
	v_mfma_f32_16x16x32_bf16 v[106:109], v[158:161], v[186:189], v[106:109]
	v_mfma_f32_16x16x32_bf16 v[94:97], v[150:153], v[182:185], v[94:97]
	v_mfma_f32_16x16x32_bf16 v[90:93], v[158:161], v[182:185], v[90:93]
	v_mfma_f32_16x16x32_bf16 v[78:81], v[150:153], v[178:181], v[78:81]
	v_mfma_f32_16x16x32_bf16 v[74:77], v[158:161], v[178:181], v[74:77]
	s_setprio 1
	s_setprio 0
	v_mfma_f32_16x16x32_bf16 v[118:121], v[130:133], v[174:177], v[118:121]
	v_mfma_f32_16x16x32_bf16 v[114:117], v[138:141], v[174:177], v[114:117]
	v_mfma_f32_16x16x32_bf16 v[102:105], v[130:133], v[170:173], v[102:105]
	v_mfma_f32_16x16x32_bf16 v[98:101], v[138:141], v[170:173], v[98:101]
	v_mfma_f32_16x16x32_bf16 v[86:89], v[130:133], v[166:169], v[86:89]
	v_mfma_f32_16x16x32_bf16 v[82:85], v[138:141], v[166:169], v[82:85]
	v_mfma_f32_16x16x32_bf16 v[70:73], v[130:133], v[162:165], v[70:73]
	v_mfma_f32_16x16x32_bf16 v[66:69], v[138:141], v[162:165], v[66:69]
	v_mfma_f32_16x16x32_bf16 v[118:121], v[134:137], v[190:193], v[118:121]
	v_mfma_f32_16x16x32_bf16 v[114:117], v[142:145], v[190:193], v[114:117]
	v_mfma_f32_16x16x32_bf16 v[102:105], v[134:137], v[186:189], v[102:105]
	v_mfma_f32_16x16x32_bf16 v[98:101], v[142:145], v[186:189], v[98:101]
	s_barrier
	v_mfma_f32_16x16x32_bf16 v[86:89], v[134:137], v[182:185], v[86:89]
	v_mfma_f32_16x16x32_bf16 v[82:85], v[142:145], v[182:185], v[82:85]
	v_mfma_f32_16x16x32_bf16 v[70:73], v[134:137], v[178:181], v[70:73]
	v_mfma_f32_16x16x32_bf16 v[66:69], v[142:145], v[178:181], v[66:69]
	s_setprio 1
	s_and_b64 vcc, exec, s[42:43]
	s_cbranch_vccnz .LBB0_565
	ds_read_b128 v[174:177], v229 offset:49152
	ds_read_b128 v[190:193], v229 offset:50176
	ds_read_b128 v[170:173], v229 offset:51200
	ds_read_b128 v[186:189], v229 offset:52224
	ds_read_b128 v[166:169], v229 offset:53248
	ds_read_b128 v[182:185], v229 offset:54272
	ds_read_b128 v[162:165], v229 offset:55296
	ds_read_b128 v[178:181], v229 offset:56320

.LBB0_761:
	s_mov_b32 m0, s14
	s_nop 0
	global_load_lds_dwordx4 v194, s[100:101]
	s_mov_b32 m0, s15
	s_nop 0
	global_load_lds_dwordx4 v196, s[100:101]
	ds_read_b128 v[130:133], v237
	ds_read_b128 v[134:137], v237 offset:1024
	ds_read_b128 v[138:141], v237 offset:2048
	ds_read_b128 v[142:145], v237 offset:3072
	ds_read_b128 v[146:149], v238
	ds_read_b128 v[150:153], v238 offset:1024
	ds_read_b128 v[154:157], v238 offset:2048
	ds_read_b128 v[158:161], v238 offset:3072
	s_add_u32 s48, s0, 0x21c000
	s_addc_u32 s49, s1, 0
	s_cmp_eq_u32 s67, 28
	s_cselect_b32 s42, s55, s62
	s_cselect_b32 s43, s29, s63
	s_cselect_b32 s52, s45, s48
	s_cselect_b32 s53, s31, s49
	s_add_u32 s50, s42, 0xe0000
	s_addc_u32 s51, s43, 0
	s_add_u32 s48, s52, 0x220000
	s_addc_u32 s49, s53, 0
	v_lshl_add_u64 v[208:209], s[0:1], 0, v[202:203]
	s_add_i32 m0, s9, 0xc000
	ds_read_b128 v[162:165], v239
	ds_read_b128 v[166:169], v239 offset:1024
	ds_read_b128 v[170:173], v239 offset:2048
	ds_read_b128 v[174:177], v239 offset:3072
	ds_read_b128 v[178:181], v239 offset:4096
	ds_read_b128 v[182:185], v239 offset:5120
	ds_read_b128 v[186:189], v239 offset:6144
	ds_read_b128 v[190:193], v239 offset:7168
	global_load_lds_dwordx4 v[208:209], off
	v_lshl_add_u64 v[208:209], s[0:1], 0, v[200:201]
	s_add_i32 m0, s9, 0xe000
	s_nop 0
	global_load_lds_dwordx4 v[208:209], off
	s_waitcnt vmcnt(8)
	s_waitcnt lgkmcnt(0)
	s_barrier
	s_setprio 0
	s_waitcnt lgkmcnt(0)
	v_mfma_f32_16x16x32_bf16 v[126:129], v[130:133], v[162:165], v[126:129]
	v_mfma_f32_16x16x32_bf16 v[122:125], v[138:141], v[162:165], v[122:125]
	v_mfma_f32_16x16x32_bf16 v[118:121], v[130:133], v[170:173], v[118:121]
	v_mfma_f32_16x16x32_bf16 v[114:117], v[138:141], v[170:173], v[114:117]
	v_mfma_f32_16x16x32_bf16 v[110:113], v[130:133], v[178:181], v[110:113]
	v_mfma_f32_16x16x32_bf16 v[106:109], v[138:141], v[178:181], v[106:109]
	v_mfma_f32_16x16x32_bf16 v[102:105], v[130:133], v[186:189], v[102:105]
	v_mfma_f32_16x16x32_bf16 v[98:101], v[138:141], v[186:189], v[98:101]
	v_mfma_f32_16x16x32_bf16 v[126:129], v[134:137], v[166:169], v[126:129]
	v_mfma_f32_16x16x32_bf16 v[122:125], v[142:145], v[166:169], v[122:125]
	v_mfma_f32_16x16x32_bf16 v[118:121], v[134:137], v[174:177], v[118:121]
	v_mfma_f32_16x16x32_bf16 v[114:117], v[142:145], v[174:177], v[114:117]
	v_mfma_f32_16x16x32_bf16 v[110:113], v[134:137], v[182:185], v[110:113]
	v_mfma_f32_16x16x32_bf16 v[106:109], v[142:145], v[182:185], v[106:109]
	v_mfma_f32_16x16x32_bf16 v[102:105], v[134:137], v[190:193], v[102:105]
	v_mfma_f32_16x16x32_bf16 v[98:101], v[142:145], v[190:193], v[98:101]
	s_setprio 1
	s_setprio 0
	v_mfma_f32_16x16x32_bf16 v[62:65], v[146:149], v[162:165], v[62:65]
	s_add_u32 s60, s52, 0x4000
	s_addc_u32 s61, s53, 0
	v_mfma_f32_16x16x32_bf16 v[58:61], v[154:157], v[162:165], v[58:61]
	v_mfma_f32_16x16x32_bf16 v[54:57], v[146:149], v[170:173], v[54:57]
	v_mfma_f32_16x16x32_bf16 v[50:53], v[154:157], v[170:173], v[50:53]
	v_mfma_f32_16x16x32_bf16 v[46:49], v[146:149], v[178:181], v[46:49]
	v_mfma_f32_16x16x32_bf16 v[42:45], v[154:157], v[178:181], v[42:45]
	v_mfma_f32_16x16x32_bf16 v[38:41], v[146:149], v[186:189], v[38:41]
	v_mfma_f32_16x16x32_bf16 v[34:37], v[154:157], v[186:189], v[34:37]
	v_mfma_f32_16x16x32_bf16 v[62:65], v[150:153], v[166:169], v[62:65]
	v_mfma_f32_16x16x32_bf16 v[58:61], v[158:161], v[166:169], v[58:61]
	v_mfma_f32_16x16x32_bf16 v[54:57], v[150:153], v[174:177], v[54:57]
	v_mfma_f32_16x16x32_bf16 v[50:53], v[158:161], v[174:177], v[50:53]
	s_barrier
	v_mfma_f32_16x16x32_bf16 v[46:49], v[150:153], v[182:185], v[46:49]
	v_mfma_f32_16x16x32_bf16 v[42:45], v[158:161], v[182:185], v[42:45]
	v_mfma_f32_16x16x32_bf16 v[38:41], v[150:153], v[190:193], v[38:41]
	v_mfma_f32_16x16x32_bf16 v[34:37], v[158:161], v[190:193], v[34:37]
	s_setprio 1
	s_add_i32 s68, s16, s8
	s_mov_b32 m0, s68
	ds_read_b128 v[162:165], v239 offset:16384
	ds_read_b128 v[166:169], v239 offset:17408
	ds_read_b128 v[170:173], v239 offset:18432
	ds_read_b128 v[174:177], v239 offset:19456
	ds_read_b128 v[178:181], v239 offset:20480
	ds_read_b128 v[182:185], v239 offset:21504
	ds_read_b128 v[186:189], v239 offset:22528
	ds_read_b128 v[190:193], v239 offset:23552
	global_load_lds_dwordx4 v194, s[42:43]
	s_add_i32 m0, s68, 0x2000
	s_add_u32 s68, s42, 0x4000
	s_addc_u32 s69, s43, 0
	s_add_i32 s70, s17, s8
	global_load_lds_dwordx4 v196, s[42:43]
	s_mov_b32 m0, s70
	s_nop 0
	global_load_lds_dwordx4 v194, s[68:69]
	s_add_i32 m0, s70, 0x2000
	s_nop 0
	global_load_lds_dwordx4 v196, s[68:69]
	s_mov_b64 s[98:99], s[52:53]
	s_waitcnt vmcnt(6)
	s_waitcnt lgkmcnt(0)
	s_barrier
	s_setprio 0
	s_waitcnt lgkmcnt(0)
	v_mfma_f32_16x16x32_bf16 v[94:97], v[130:133], v[162:165], v[94:97]
	v_mfma_f32_16x16x32_bf16 v[90:93], v[138:141], v[162:165], v[90:93]
	v_mfma_f32_16x16x32_bf16 v[86:89], v[130:133], v[170:173], v[86:89]
	v_mfma_f32_16x16x32_bf16 v[82:85], v[138:141], v[170:173], v[82:85]
	v_mfma_f32_16x16x32_bf16 v[78:81], v[130:133], v[178:181], v[78:81]
	v_mfma_f32_16x16x32_bf16 v[74:77], v[138:141], v[178:181], v[74:77]
	v_mfma_f32_16x16x32_bf16 v[70:73], v[130:133], v[186:189], v[70:73]
	v_mfma_f32_16x16x32_bf16 v[66:69], v[138:141], v[186:189], v[66:69]
	v_mfma_f32_16x16x32_bf16 v[94:97], v[134:137], v[166:169], v[94:97]
	v_mfma_f32_16x16x32_bf16 v[90:93], v[142:145], v[166:169], v[90:93]
	v_mfma_f32_16x16x32_bf16 v[86:89], v[134:137], v[174:177], v[86:89]
	v_mfma_f32_16x16x32_bf16 v[82:85], v[142:145], v[174:177], v[82:85]
	v_mfma_f32_16x16x32_bf16 v[78:81], v[134:137], v[182:185], v[78:81]
	v_mfma_f32_16x16x32_bf16 v[74:77], v[142:145], v[182:185], v[74:77]
	v_mfma_f32_16x16x32_bf16 v[70:73], v[134:137], v[190:193], v[70:73]
	v_mfma_f32_16x16x32_bf16 v[66:69], v[142:145], v[190:193], v[66:69]
	s_setprio 1
	s_setprio 0
	v_mfma_f32_16x16x32_bf16 v[30:33], v[146:149], v[162:165], v[30:33]
	v_mfma_f32_16x16x32_bf16 v[26:29], v[154:157], v[162:165], v[26:29]
	v_mfma_f32_16x16x32_bf16 v[22:25], v[146:149], v[170:173], v[22:25]
	v_mfma_f32_16x16x32_bf16 v[18:21], v[154:157], v[170:173], v[18:21]
	v_mfma_f32_16x16x32_bf16 v[14:17], v[146:149], v[178:181], v[14:17]
	v_mfma_f32_16x16x32_bf16 v[10:13], v[154:157], v[178:181], v[10:13]
	v_mfma_f32_16x16x32_bf16 v[6:9], v[146:149], v[186:189], v[6:9]
	v_mfma_f32_16x16x32_bf16 v[2:5], v[154:157], v[186:189], v[2:5]
	v_mfma_f32_16x16x32_bf16 v[30:33], v[150:153], v[166:169], v[30:33]
	v_mfma_f32_16x16x32_bf16 v[26:29], v[158:161], v[166:169], v[26:29]
	v_mfma_f32_16x16x32_bf16 v[22:25], v[150:153], v[174:177], v[22:25]
	v_mfma_f32_16x16x32_bf16 v[18:21], v[158:161], v[174:177], v[18:21]
	s_barrier
	s_mov_b32 m0, s9
	s_nop 0
	global_load_lds_dwordx4 v194, s[98:99]
	s_mov_b32 m0, s10
	s_nop 0
	global_load_lds_dwordx4 v196, s[98:99]
	v_mfma_f32_16x16x32_bf16 v[14:17], v[150:153], v[182:185], v[14:17]
	v_mfma_f32_16x16x32_bf16 v[10:13], v[158:161], v[182:185], v[10:13]
	v_mfma_f32_16x16x32_bf16 v[6:9], v[150:153], v[190:193], v[6:9]
	v_mfma_f32_16x16x32_bf16 v[2:5], v[158:161], v[190:193], v[2:5]
	s_setprio 1
	s_add_i32 s52, 0, 0x18000
	s_add_i32 s53, 0, 0x1c000
	v_add_u32_e32 v142, s52, v228
	v_add_u32_e32 v158, s53, v228
	ds_read_b128 v[130:133], v142
	ds_read_b128 v[134:137], v142 offset:1024
	ds_read_b128 v[138:141], v142 offset:2048
	ds_read_b128 v[142:145], v142 offset:3072
	ds_read_b128 v[146:149], v158
	ds_read_b128 v[150:153], v158 offset:1024
	ds_read_b128 v[154:157], v158 offset:2048
	ds_read_b128 v[158:161], v158 offset:3072
	s_mov_b32 m0, s11
	ds_read_b128 v[162:165], v239 offset:32768
	ds_read_b128 v[166:169], v239 offset:33792
	ds_read_b128 v[170:173], v239 offset:34816
	ds_read_b128 v[174:177], v239 offset:35840
	ds_read_b128 v[178:181], v239 offset:36864
	ds_read_b128 v[182:185], v239 offset:37888
	ds_read_b128 v[186:189], v239 offset:38912
	ds_read_b128 v[190:193], v239 offset:39936
	global_load_lds_dwordx4 v194, s[60:61]
	s_mov_b32 m0, s12
	s_nop 0
	global_load_lds_dwordx4 v196, s[60:61]
	s_waitcnt vmcnt(8)
	s_waitcnt lgkmcnt(0)
	s_barrier
	s_setprio 0
	s_waitcnt lgkmcnt(0)
	v_mfma_f32_16x16x32_bf16 v[126:129], v[130:133], v[162:165], v[126:129]
	v_mfma_f32_16x16x32_bf16 v[122:125], v[138:141], v[162:165], v[122:125]
	v_mfma_f32_16x16x32_bf16 v[118:121], v[130:133], v[170:173], v[118:121]
	v_mfma_f32_16x16x32_bf16 v[114:117], v[138:141], v[170:173], v[114:117]
	v_mfma_f32_16x16x32_bf16 v[110:113], v[130:133], v[178:181], v[110:113]
	v_mfma_f32_16x16x32_bf16 v[106:109], v[138:141], v[178:181], v[106:109]
	v_mfma_f32_16x16x32_bf16 v[102:105], v[130:133], v[186:189], v[102:105]
	v_mfma_f32_16x16x32_bf16 v[98:101], v[138:141], v[186:189], v[98:101]
	v_mfma_f32_16x16x32_bf16 v[126:129], v[134:137], v[166:169], v[126:129]
	v_mfma_f32_16x16x32_bf16 v[122:125], v[142:145], v[166:169], v[122:125]
	v_mfma_f32_16x16x32_bf16 v[118:121], v[134:137], v[174:177], v[118:121]
	v_mfma_f32_16x16x32_bf16 v[114:117], v[142:145], v[174:177], v[114:117]
	v_mfma_f32_16x16x32_bf16 v[110:113], v[134:137], v[182:185], v[110:113]
	v_mfma_f32_16x16x32_bf16 v[106:109], v[142:145], v[182:185], v[106:109]
	v_mfma_f32_16x16x32_bf16 v[102:105], v[134:137], v[190:193], v[102:105]
	v_mfma_f32_16x16x32_bf16 v[98:101], v[142:145], v[190:193], v[98:101]
	s_setprio 1
	s_setprio 0
	v_mfma_f32_16x16x32_bf16 v[62:65], v[146:149], v[162:165], v[62:65]
	v_mfma_f32_16x16x32_bf16 v[58:61], v[154:157], v[162:165], v[58:61]
	v_mfma_f32_16x16x32_bf16 v[54:57], v[146:149], v[170:173], v[54:57]
	v_mfma_f32_16x16x32_bf16 v[50:53], v[154:157], v[170:173], v[50:53]
	v_mfma_f32_16x16x32_bf16 v[46:49], v[146:149], v[178:181], v[46:49]
	v_mfma_f32_16x16x32_bf16 v[42:45], v[154:157], v[178:181], v[42:45]
	v_mfma_f32_16x16x32_bf16 v[38:41], v[146:149], v[186:189], v[38:41]
	v_mfma_f32_16x16x32_bf16 v[34:37], v[154:157], v[186:189], v[34:37]
	v_mfma_f32_16x16x32_bf16 v[62:65], v[150:153], v[166:169], v[62:65]
	v_mfma_f32_16x16x32_bf16 v[58:61], v[158:161], v[166:169], v[58:61]
	v_mfma_f32_16x16x32_bf16 v[54:57], v[150:153], v[174:177], v[54:57]
	v_mfma_f32_16x16x32_bf16 v[50:53], v[158:161], v[174:177], v[50:53]
	s_barrier
	v_mfma_f32_16x16x32_bf16 v[46:49], v[150:153], v[182:185], v[46:49]
	v_mfma_f32_16x16x32_bf16 v[42:45], v[158:161], v[182:185], v[42:45]
	v_mfma_f32_16x16x32_bf16 v[38:41], v[150:153], v[190:193], v[38:41]
	v_mfma_f32_16x16x32_bf16 v[34:37], v[158:161], v[190:193], v[34:37]
	s_setprio 1
	s_add_i32 s52, s52, s8
	s_mov_b32 m0, s52
	ds_read_b128 v[162:165], v239 offset:49152
	ds_read_b128 v[166:169], v239 offset:50176
	ds_read_b128 v[170:173], v239 offset:51200
	ds_read_b128 v[174:177], v239 offset:52224
	ds_read_b128 v[178:181], v239 offset:53248
	ds_read_b128 v[182:185], v239 offset:54272
	ds_read_b128 v[186:189], v239 offset:55296
	ds_read_b128 v[190:193], v239 offset:56320
	global_load_lds_dwordx4 v194, s[50:51]
	s_add_i32 m0, s52, 0x2000
	s_add_u32 s42, s42, 0xe4000
	v_lshl_add_u64 v[208:209], s[50:51], 0, v[196:197]
	s_addc_u32 s43, s43, 0
	s_add_i32 s50, s53, s8
	global_load_lds_dwordx4 v[208:209], off
	s_mov_b32 m0, s50
	s_nop 0
	global_load_lds_dwordx4 v194, s[42:43]
	s_add_i32 m0, s50, 0x2000
	s_nop 0
	global_load_lds_dwordx4 v196, s[42:43]
	s_mov_b64 s[100:101], s[48:49]
	s_waitcnt vmcnt(6)
	s_waitcnt lgkmcnt(0)
	s_barrier
	s_setprio 0
	s_waitcnt lgkmcnt(0)
	v_mfma_f32_16x16x32_bf16 v[94:97], v[130:133], v[162:165], v[94:97]
	v_mfma_f32_16x16x32_bf16 v[90:93], v[138:141], v[162:165], v[90:93]
	v_mfma_f32_16x16x32_bf16 v[86:89], v[130:133], v[170:173], v[86:89]
	v_mfma_f32_16x16x32_bf16 v[82:85], v[138:141], v[170:173], v[82:85]
	v_mfma_f32_16x16x32_bf16 v[78:81], v[130:133], v[178:181], v[78:81]
	v_mfma_f32_16x16x32_bf16 v[74:77], v[138:141], v[178:181], v[74:77]
	v_mfma_f32_16x16x32_bf16 v[70:73], v[130:133], v[186:189], v[70:73]
	v_mfma_f32_16x16x32_bf16 v[66:69], v[138:141], v[186:189], v[66:69]
	v_mfma_f32_16x16x32_bf16 v[94:97], v[134:137], v[166:169], v[94:97]
	v_mfma_f32_16x16x32_bf16 v[90:93], v[142:145], v[166:169], v[90:93]
	v_mfma_f32_16x16x32_bf16 v[86:89], v[134:137], v[174:177], v[86:89]
	v_mfma_f32_16x16x32_bf16 v[82:85], v[142:145], v[174:177], v[82:85]
	v_mfma_f32_16x16x32_bf16 v[78:81], v[134:137], v[182:185], v[78:81]
	v_mfma_f32_16x16x32_bf16 v[74:77], v[142:145], v[182:185], v[74:77]
	v_mfma_f32_16x16x32_bf16 v[70:73], v[134:137], v[190:193], v[70:73]
	v_mfma_f32_16x16x32_bf16 v[66:69], v[142:145], v[190:193], v[66:69]
	s_setprio 1
	s_setprio 0
	v_mfma_f32_16x16x32_bf16 v[30:33], v[146:149], v[162:165], v[30:33]
	v_mfma_f32_16x16x32_bf16 v[26:29], v[154:157], v[162:165], v[26:29]
	v_mfma_f32_16x16x32_bf16 v[22:25], v[146:149], v[170:173], v[22:25]
	v_mfma_f32_16x16x32_bf16 v[18:21], v[154:157], v[170:173], v[18:21]
	v_mfma_f32_16x16x32_bf16 v[14:17], v[146:149], v[178:181], v[14:17]
	v_mfma_f32_16x16x32_bf16 v[10:13], v[154:157], v[178:181], v[10:13]
	v_mfma_f32_16x16x32_bf16 v[6:9], v[146:149], v[186:189], v[6:9]
	v_mfma_f32_16x16x32_bf16 v[2:5], v[154:157], v[186:189], v[2:5]
	v_mfma_f32_16x16x32_bf16 v[30:33], v[150:153], v[166:169], v[30:33]
	v_mfma_f32_16x16x32_bf16 v[26:29], v[158:161], v[166:169], v[26:29]
	v_mfma_f32_16x16x32_bf16 v[22:25], v[150:153], v[174:177], v[22:25]
	v_mfma_f32_16x16x32_bf16 v[18:21], v[158:161], v[174:177], v[18:21]
	s_barrier
	v_mfma_f32_16x16x32_bf16 v[14:17], v[150:153], v[182:185], v[14:17]
	v_mfma_f32_16x16x32_bf16 v[10:13], v[158:161], v[182:185], v[10:13]
	v_mfma_f32_16x16x32_bf16 v[6:9], v[150:153], v[190:193], v[6:9]
	v_mfma_f32_16x16x32_bf16 v[2:5], v[158:161], v[190:193], v[2:5]
	s_setprio 1
	s_add_i32 s67, s67, 2
	s_add_u32 s62, s62, 0x1c0000
	s_addc_u32 s63, s63, 0
	s_add_u32 s0, s0, 0x440000
	s_addc_u32 s1, s1, 0
	s_cmp_gt_u32 s67, 29
	s_cbranch_scc0 .LBB0_761
	s_and_b64 vcc, exec, s[26:27]
	s_cbranch_vccz .LBB0_764
	s_barrier

.LBB0_903:
	s_mov_b32 m0, s23
	s_nop 0
	global_load_lds_dwordx4 v194, s[100:101]
	s_mov_b32 m0, s31
	s_nop 0
	global_load_lds_dwordx4 v196, s[100:101]
	ds_read_b128 v[146:149], v225
	ds_read_b128 v[150:153], v225 offset:1024
	ds_read_b128 v[154:157], v225 offset:2048
	ds_read_b128 v[158:161], v225 offset:3072
	ds_read_b128 v[130:133], v227
	ds_read_b128 v[134:137], v227 offset:1024
	ds_read_b128 v[138:141], v227 offset:2048
	ds_read_b128 v[142:145], v227 offset:3072
	v_lshl_add_u64 v[234:235], v[210:211], 0, s[62:63]
	s_add_i32 m0, s8, 0xc000
	s_waitcnt lgkmcnt(0)
	ds_read_b128 v[174:177], v228
	ds_read_b128 v[190:193], v228 offset:1024
	ds_read_b128 v[170:173], v228 offset:2048
	ds_read_b128 v[186:189], v228 offset:3072
	ds_read_b128 v[166:169], v228 offset:4096
	ds_read_b128 v[182:185], v228 offset:5120
	ds_read_b128 v[162:165], v228 offset:6144
	ds_read_b128 v[178:181], v228 offset:7168
	global_load_lds_dwordx4 v[234:235], off
	v_lshl_add_u64 v[234:235], v[212:213], 0, s[62:63]
	s_add_i32 m0, s8, 0xe000
	s_nop 0
	global_load_lds_dwordx4 v[234:235], off
	s_waitcnt vmcnt(8)
	s_waitcnt lgkmcnt(0)
	s_barrier
	s_setprio 0
	s_waitcnt lgkmcnt(0)
	v_mfma_f32_16x16x32_bf16 v[126:129], v[146:149], v[174:177], v[126:129]
	v_mfma_f32_16x16x32_bf16 v[122:125], v[154:157], v[174:177], v[122:125]
	v_mfma_f32_16x16x32_bf16 v[118:121], v[146:149], v[170:173], v[118:121]
	v_mfma_f32_16x16x32_bf16 v[114:117], v[154:157], v[170:173], v[114:117]
	v_mfma_f32_16x16x32_bf16 v[110:113], v[146:149], v[166:169], v[110:113]
	v_mfma_f32_16x16x32_bf16 v[106:109], v[154:157], v[166:169], v[106:109]
	v_mfma_f32_16x16x32_bf16 v[102:105], v[146:149], v[162:165], v[102:105]
	v_mfma_f32_16x16x32_bf16 v[98:101], v[154:157], v[162:165], v[98:101]
	v_mfma_f32_16x16x32_bf16 v[126:129], v[150:153], v[190:193], v[126:129]
	v_mfma_f32_16x16x32_bf16 v[122:125], v[158:161], v[190:193], v[122:125]
	v_mfma_f32_16x16x32_bf16 v[118:121], v[150:153], v[186:189], v[118:121]
	v_mfma_f32_16x16x32_bf16 v[114:117], v[158:161], v[186:189], v[114:117]
	v_mfma_f32_16x16x32_bf16 v[110:113], v[150:153], v[182:185], v[110:113]
	v_mfma_f32_16x16x32_bf16 v[106:109], v[158:161], v[182:185], v[106:109]
	v_mfma_f32_16x16x32_bf16 v[102:105], v[150:153], v[178:181], v[102:105]
	v_mfma_f32_16x16x32_bf16 v[98:101], v[158:161], v[178:181], v[98:101]
	s_setprio 1
	s_setprio 0
	v_mfma_f32_16x16x32_bf16 v[94:97], v[130:133], v[174:177], v[94:97]
	v_mfma_f32_16x16x32_bf16 v[90:93], v[138:141], v[174:177], v[90:93]
	v_mfma_f32_16x16x32_bf16 v[86:89], v[130:133], v[170:173], v[86:89]
	v_mfma_f32_16x16x32_bf16 v[82:85], v[138:141], v[170:173], v[82:85]
	v_mfma_f32_16x16x32_bf16 v[78:81], v[130:133], v[166:169], v[78:81]
	v_mfma_f32_16x16x32_bf16 v[74:77], v[138:141], v[166:169], v[74:77]
	v_mfma_f32_16x16x32_bf16 v[70:73], v[130:133], v[162:165], v[70:73]
	v_mfma_f32_16x16x32_bf16 v[66:69], v[138:141], v[162:165], v[66:69]
	v_mfma_f32_16x16x32_bf16 v[94:97], v[134:137], v[190:193], v[94:97]
	v_mfma_f32_16x16x32_bf16 v[90:93], v[142:145], v[190:193], v[90:93]
	v_mfma_f32_16x16x32_bf16 v[86:89], v[134:137], v[186:189], v[86:89]
	v_mfma_f32_16x16x32_bf16 v[82:85], v[142:145], v[186:189], v[82:85]
	s_barrier
	v_mfma_f32_16x16x32_bf16 v[78:81], v[134:137], v[182:185], v[78:81]
	v_mfma_f32_16x16x32_bf16 v[74:77], v[142:145], v[182:185], v[74:77]
	v_mfma_f32_16x16x32_bf16 v[70:73], v[134:137], v[178:181], v[70:73]
	v_mfma_f32_16x16x32_bf16 v[66:69], v[142:145], v[178:181], v[66:69]
	s_setprio 1
	v_cmp_ne_u32_e64 s[42:43], 1, v233
	s_andn2_b64 vcc, exec, s[44:45]
	s_cbranch_vccnz .LBB0_905
	ds_read_b128 v[174:177], v228 offset:16384
	ds_read_b128 v[190:193], v228 offset:17408
	ds_read_b128 v[170:173], v228 offset:18432
	ds_read_b128 v[186:189], v228 offset:19456
	ds_read_b128 v[166:169], v228 offset:20480
	ds_read_b128 v[182:185], v228 offset:21504
	ds_read_b128 v[162:165], v228 offset:22528
	ds_read_b128 v[178:181], v228 offset:23552

.LBB0_907:
	s_and_b64 vcc, s[40:41], s[72:73]
	v_cndmask_b32_e64 v131, v209, 0, vcc
	v_cndmask_b32_e32 v130, v208, v198, vcc
	v_lshl_add_u64 v[234:235], s[70:71], 0, v[130:131]
	s_barrier
	s_mov_b32 m0, s8
	s_nop 0
	global_load_lds_dwordx4 v194, s[98:99]
	s_mov_b32 m0, s13
	s_nop 0
	global_load_lds_dwordx4 v196, s[98:99]
	v_add_u32_e32 v130, 0x18000, v224
	v_add_u32_e32 v142, 0x1c000, v224
	ds_read_b128 v[146:149], v130
	ds_read_b128 v[150:153], v130 offset:1024
	ds_read_b128 v[154:157], v130 offset:2048
	ds_read_b128 v[158:161], v130 offset:3072
	ds_read_b128 v[130:133], v142
	ds_read_b128 v[134:137], v142 offset:1024
	ds_read_b128 v[138:141], v142 offset:2048
	ds_read_b128 v[142:145], v142 offset:3072
	s_mov_b32 m0, s14
	v_lshl_add_u64 v[236:237], v[234:235], 0, v[194:195]
	s_waitcnt lgkmcnt(0)
	ds_read_b128 v[174:177], v228 offset:32768
	ds_read_b128 v[190:193], v228 offset:33792
	ds_read_b128 v[170:173], v228 offset:34816
	ds_read_b128 v[186:189], v228 offset:35840
	ds_read_b128 v[166:169], v228 offset:36864
	ds_read_b128 v[182:185], v228 offset:37888
	ds_read_b128 v[162:165], v228 offset:38912
	ds_read_b128 v[178:181], v228 offset:39936
	global_load_lds_dwordx4 v[236:237], off
	v_lshl_add_u64 v[234:235], v[234:235], 0, v[196:197]
	s_mov_b32 m0, s15
	s_nop 0
	global_load_lds_dwordx4 v[234:235], off
	s_waitcnt vmcnt(8)
	s_waitcnt lgkmcnt(0)
	s_barrier
	s_setprio 0
	s_waitcnt lgkmcnt(0)
	v_mfma_f32_16x16x32_bf16 v[126:129], v[146:149], v[174:177], v[126:129]
	v_mfma_f32_16x16x32_bf16 v[122:125], v[154:157], v[174:177], v[122:125]
	v_mfma_f32_16x16x32_bf16 v[118:121], v[146:149], v[170:173], v[118:121]
	v_mfma_f32_16x16x32_bf16 v[114:117], v[154:157], v[170:173], v[114:117]
	v_mfma_f32_16x16x32_bf16 v[110:113], v[146:149], v[166:169], v[110:113]
	v_mfma_f32_16x16x32_bf16 v[106:109], v[154:157], v[166:169], v[106:109]
	v_mfma_f32_16x16x32_bf16 v[102:105], v[146:149], v[162:165], v[102:105]
	v_mfma_f32_16x16x32_bf16 v[98:101], v[154:157], v[162:165], v[98:101]
	v_mfma_f32_16x16x32_bf16 v[126:129], v[150:153], v[190:193], v[126:129]
	v_mfma_f32_16x16x32_bf16 v[122:125], v[158:161], v[190:193], v[122:125]
	v_mfma_f32_16x16x32_bf16 v[118:121], v[150:153], v[186:189], v[118:121]
	v_mfma_f32_16x16x32_bf16 v[114:117], v[158:161], v[186:189], v[114:117]
	v_mfma_f32_16x16x32_bf16 v[110:113], v[150:153], v[182:185], v[110:113]
	v_mfma_f32_16x16x32_bf16 v[106:109], v[158:161], v[182:185], v[106:109]
	v_mfma_f32_16x16x32_bf16 v[102:105], v[150:153], v[178:181], v[102:105]
	v_mfma_f32_16x16x32_bf16 v[98:101], v[158:161], v[178:181], v[98:101]
	s_setprio 1
	s_setprio 0
	v_mfma_f32_16x16x32_bf16 v[94:97], v[130:133], v[174:177], v[94:97]
	v_mfma_f32_16x16x32_bf16 v[90:93], v[138:141], v[174:177], v[90:93]
	v_mfma_f32_16x16x32_bf16 v[86:89], v[130:133], v[170:173], v[86:89]
	v_mfma_f32_16x16x32_bf16 v[82:85], v[138:141], v[170:173], v[82:85]
	v_mfma_f32_16x16x32_bf16 v[78:81], v[130:133], v[166:169], v[78:81]
	v_mfma_f32_16x16x32_bf16 v[74:77], v[138:141], v[166:169], v[74:77]
	v_mfma_f32_16x16x32_bf16 v[70:73], v[130:133], v[162:165], v[70:73]
	v_mfma_f32_16x16x32_bf16 v[66:69], v[138:141], v[162:165], v[66:69]
	v_mfma_f32_16x16x32_bf16 v[94:97], v[134:137], v[190:193], v[94:97]
	v_mfma_f32_16x16x32_bf16 v[90:93], v[142:145], v[190:193], v[90:93]
	v_mfma_f32_16x16x32_bf16 v[86:89], v[134:137], v[186:189], v[86:89]
	v_mfma_f32_16x16x32_bf16 v[82:85], v[142:145], v[186:189], v[82:85]
	s_barrier
	v_mfma_f32_16x16x32_bf16 v[78:81], v[134:137], v[182:185], v[78:81]
	v_mfma_f32_16x16x32_bf16 v[74:77], v[142:145], v[182:185], v[74:77]
	v_mfma_f32_16x16x32_bf16 v[70:73], v[134:137], v[178:181], v[70:73]
	v_mfma_f32_16x16x32_bf16 v[66:69], v[142:145], v[178:181], v[66:69]
	s_setprio 1
	s_and_b64 vcc, exec, s[42:43]
	s_cbranch_vccnz .LBB0_909
	ds_read_b128 v[174:177], v228 offset:49152
	ds_read_b128 v[190:193], v228 offset:50176
	ds_read_b128 v[170:173], v228 offset:51200
	ds_read_b128 v[186:189], v228 offset:52224
	ds_read_b128 v[166:169], v228 offset:53248
	ds_read_b128 v[182:185], v228 offset:54272
	ds_read_b128 v[162:165], v228 offset:55296
	ds_read_b128 v[178:181], v228 offset:56320

.LBB0_1289:
	s_mov_b32 m0, s27
	s_nop 0
	global_load_lds_dwordx4 v194, s[100:101]
	s_mov_b32 m0, s54
	s_nop 0
	global_load_lds_dwordx4 v196, s[100:101]
	v_add_u32_e32 v142, 0x14000, v229
	ds_read_b128 v[146:149], v230
	ds_read_b128 v[150:153], v230 offset:1024
	ds_read_b128 v[154:157], v230 offset:2048
	ds_read_b128 v[158:161], v230 offset:3072
	ds_read_b128 v[130:133], v142
	ds_read_b128 v[134:137], v142 offset:1024
	ds_read_b128 v[138:141], v142 offset:2048
	ds_read_b128 v[142:145], v142 offset:3072
	v_lshl_add_u64 v[234:235], v[222:223], 0, s[48:49]
	s_add_i32 m0, s8, 0xc000
	s_waitcnt lgkmcnt(0)
	ds_read_b128 v[174:177], v231
	ds_read_b128 v[190:193], v231 offset:1024
	ds_read_b128 v[170:173], v231 offset:2048
	ds_read_b128 v[186:189], v231 offset:3072
	ds_read_b128 v[166:169], v231 offset:4096
	ds_read_b128 v[182:185], v231 offset:5120
	ds_read_b128 v[162:165], v231 offset:6144
	ds_read_b128 v[178:181], v231 offset:7168
	global_load_lds_dwordx4 v[234:235], off
	v_lshl_add_u64 v[234:235], v[224:225], 0, s[48:49]
	s_add_i32 m0, s8, 0xe000
	s_nop 0
	global_load_lds_dwordx4 v[234:235], off
	s_waitcnt vmcnt(8)
	s_waitcnt lgkmcnt(0)
	s_barrier
	s_setprio 0
	s_waitcnt lgkmcnt(0)
	v_mfma_f32_16x16x32_bf16 v[126:129], v[146:149], v[174:177], v[126:129]
	v_mfma_f32_16x16x32_bf16 v[122:125], v[154:157], v[174:177], v[122:125]
	v_mfma_f32_16x16x32_bf16 v[118:121], v[146:149], v[170:173], v[118:121]
	v_mfma_f32_16x16x32_bf16 v[110:113], v[154:157], v[170:173], v[110:113]
	v_mfma_f32_16x16x32_bf16 v[102:105], v[146:149], v[166:169], v[102:105]
	v_mfma_f32_16x16x32_bf16 v[94:97], v[154:157], v[166:169], v[94:97]
	v_mfma_f32_16x16x32_bf16 v[86:89], v[146:149], v[162:165], v[86:89]
	v_mfma_f32_16x16x32_bf16 v[78:81], v[154:157], v[162:165], v[78:81]
	v_mfma_f32_16x16x32_bf16 v[126:129], v[150:153], v[190:193], v[126:129]
	v_mfma_f32_16x16x32_bf16 v[122:125], v[158:161], v[190:193], v[122:125]
	v_mfma_f32_16x16x32_bf16 v[118:121], v[150:153], v[186:189], v[118:121]
	v_mfma_f32_16x16x32_bf16 v[110:113], v[158:161], v[186:189], v[110:113]
	v_mfma_f32_16x16x32_bf16 v[102:105], v[150:153], v[182:185], v[102:105]
	v_mfma_f32_16x16x32_bf16 v[94:97], v[158:161], v[182:185], v[94:97]
	v_mfma_f32_16x16x32_bf16 v[86:89], v[150:153], v[178:181], v[86:89]
	v_mfma_f32_16x16x32_bf16 v[78:81], v[158:161], v[178:181], v[78:81]
	s_setprio 1
	s_setprio 0
	v_mfma_f32_16x16x32_bf16 v[114:117], v[130:133], v[174:177], v[114:117]
	v_mfma_f32_16x16x32_bf16 v[106:109], v[138:141], v[174:177], v[106:109]
	v_mfma_f32_16x16x32_bf16 v[98:101], v[130:133], v[170:173], v[98:101]
	v_mfma_f32_16x16x32_bf16 v[90:93], v[138:141], v[170:173], v[90:93]
	v_mfma_f32_16x16x32_bf16 v[82:85], v[130:133], v[166:169], v[82:85]
	v_mfma_f32_16x16x32_bf16 v[74:77], v[138:141], v[166:169], v[74:77]
	v_mfma_f32_16x16x32_bf16 v[70:73], v[130:133], v[162:165], v[70:73]
	v_mfma_f32_16x16x32_bf16 v[66:69], v[138:141], v[162:165], v[66:69]
	v_mfma_f32_16x16x32_bf16 v[114:117], v[134:137], v[190:193], v[114:117]
	v_mfma_f32_16x16x32_bf16 v[106:109], v[142:145], v[190:193], v[106:109]
	v_mfma_f32_16x16x32_bf16 v[98:101], v[134:137], v[186:189], v[98:101]
	v_mfma_f32_16x16x32_bf16 v[90:93], v[142:145], v[186:189], v[90:93]
	s_barrier
	v_mfma_f32_16x16x32_bf16 v[82:85], v[134:137], v[182:185], v[82:85]
	v_mfma_f32_16x16x32_bf16 v[74:77], v[142:145], v[182:185], v[74:77]
	v_mfma_f32_16x16x32_bf16 v[70:73], v[134:137], v[178:181], v[70:73]
	v_mfma_f32_16x16x32_bf16 v[66:69], v[142:145], v[178:181], v[66:69]
	s_setprio 1
	v_cndmask_b32_e64 v233, 0, 1, s[40:41]
	v_cmp_ne_u32_e64 s[42:43], 1, v233
	s_andn2_b64 vcc, exec, s[40:41]
	s_cbranch_vccnz .LBB0_1291
	ds_read_b128 v[174:177], v231 offset:16384
	ds_read_b128 v[190:193], v231 offset:17408
	ds_read_b128 v[170:173], v231 offset:18432
	ds_read_b128 v[186:189], v231 offset:19456
	ds_read_b128 v[166:169], v231 offset:20480
	ds_read_b128 v[182:185], v231 offset:21504
	ds_read_b128 v[162:165], v231 offset:22528
	ds_read_b128 v[178:181], v231 offset:23552

.LBB0_1293:
	s_and_b64 vcc, s[34:35], s[58:59]
	v_cndmask_b32_e64 v131, v221, 0, vcc
	v_cndmask_b32_e32 v130, v220, v198, vcc
	v_lshl_add_u64 v[234:235], s[56:57], 0, v[130:131]
	s_barrier
	s_mov_b32 m0, s8
	s_nop 0
	global_load_lds_dwordx4 v194, s[98:99]
	s_mov_b32 m0, s13
	s_nop 0
	global_load_lds_dwordx4 v196, s[98:99]
	v_add_u32_e32 v130, 0x18000, v229
	v_add_u32_e32 v142, 0x1c000, v229
	ds_read_b128 v[146:149], v130
	ds_read_b128 v[150:153], v130 offset:1024
	ds_read_b128 v[154:157], v130 offset:2048
	ds_read_b128 v[158:161], v130 offset:3072
	ds_read_b128 v[130:133], v142
	ds_read_b128 v[134:137], v142 offset:1024
	ds_read_b128 v[138:141], v142 offset:2048
	ds_read_b128 v[142:145], v142 offset:3072
	s_mov_b32 m0, s14
	v_lshl_add_u64 v[236:237], v[234:235], 0, v[194:195]
	s_waitcnt lgkmcnt(0)
	ds_read_b128 v[174:177], v231 offset:32768
	ds_read_b128 v[190:193], v231 offset:33792
	ds_read_b128 v[170:173], v231 offset:34816
	ds_read_b128 v[186:189], v231 offset:35840
	ds_read_b128 v[166:169], v231 offset:36864
	ds_read_b128 v[182:185], v231 offset:37888
	ds_read_b128 v[162:165], v231 offset:38912
	ds_read_b128 v[178:181], v231 offset:39936
	global_load_lds_dwordx4 v[236:237], off
	v_lshl_add_u64 v[234:235], v[234:235], 0, v[196:197]
	s_mov_b32 m0, s15
	s_nop 0
	global_load_lds_dwordx4 v[234:235], off
	s_waitcnt vmcnt(8)
	s_waitcnt lgkmcnt(0)
	s_barrier
	s_setprio 0
	s_waitcnt lgkmcnt(0)
	v_mfma_f32_16x16x32_bf16 v[126:129], v[146:149], v[174:177], v[126:129]
	v_mfma_f32_16x16x32_bf16 v[122:125], v[154:157], v[174:177], v[122:125]
	v_mfma_f32_16x16x32_bf16 v[118:121], v[146:149], v[170:173], v[118:121]
	v_mfma_f32_16x16x32_bf16 v[110:113], v[154:157], v[170:173], v[110:113]
	v_mfma_f32_16x16x32_bf16 v[102:105], v[146:149], v[166:169], v[102:105]
	v_mfma_f32_16x16x32_bf16 v[94:97], v[154:157], v[166:169], v[94:97]
	v_mfma_f32_16x16x32_bf16 v[86:89], v[146:149], v[162:165], v[86:89]
	v_mfma_f32_16x16x32_bf16 v[78:81], v[154:157], v[162:165], v[78:81]
	v_mfma_f32_16x16x32_bf16 v[126:129], v[150:153], v[190:193], v[126:129]
	v_mfma_f32_16x16x32_bf16 v[122:125], v[158:161], v[190:193], v[122:125]
	v_mfma_f32_16x16x32_bf16 v[118:121], v[150:153], v[186:189], v[118:121]
	v_mfma_f32_16x16x32_bf16 v[110:113], v[158:161], v[186:189], v[110:113]
	v_mfma_f32_16x16x32_bf16 v[102:105], v[150:153], v[182:185], v[102:105]
	v_mfma_f32_16x16x32_bf16 v[94:97], v[158:161], v[182:185], v[94:97]
	v_mfma_f32_16x16x32_bf16 v[86:89], v[150:153], v[178:181], v[86:89]
	v_mfma_f32_16x16x32_bf16 v[78:81], v[158:161], v[178:181], v[78:81]
	s_setprio 1
	s_setprio 0
	v_mfma_f32_16x16x32_bf16 v[114:117], v[130:133], v[174:177], v[114:117]
	v_mfma_f32_16x16x32_bf16 v[106:109], v[138:141], v[174:177], v[106:109]
	v_mfma_f32_16x16x32_bf16 v[98:101], v[130:133], v[170:173], v[98:101]
	v_mfma_f32_16x16x32_bf16 v[90:93], v[138:141], v[170:173], v[90:93]
	v_mfma_f32_16x16x32_bf16 v[82:85], v[130:133], v[166:169], v[82:85]
	v_mfma_f32_16x16x32_bf16 v[74:77], v[138:141], v[166:169], v[74:77]
	v_mfma_f32_16x16x32_bf16 v[70:73], v[130:133], v[162:165], v[70:73]
	v_mfma_f32_16x16x32_bf16 v[66:69], v[138:141], v[162:165], v[66:69]
	v_mfma_f32_16x16x32_bf16 v[114:117], v[134:137], v[190:193], v[114:117]
	v_mfma_f32_16x16x32_bf16 v[106:109], v[142:145], v[190:193], v[106:109]
	v_mfma_f32_16x16x32_bf16 v[98:101], v[134:137], v[186:189], v[98:101]
	v_mfma_f32_16x16x32_bf16 v[90:93], v[142:145], v[186:189], v[90:93]
	s_barrier
	v_mfma_f32_16x16x32_bf16 v[82:85], v[134:137], v[182:185], v[82:85]
	v_mfma_f32_16x16x32_bf16 v[74:77], v[142:145], v[182:185], v[74:77]
	v_mfma_f32_16x16x32_bf16 v[70:73], v[134:137], v[178:181], v[70:73]
	v_mfma_f32_16x16x32_bf16 v[66:69], v[142:145], v[178:181], v[66:69]
	s_setprio 1
	s_and_b64 vcc, exec, s[42:43]
	s_cbranch_vccnz .LBB0_1295
	ds_read_b128 v[174:177], v231 offset:49152
	ds_read_b128 v[190:193], v231 offset:50176
	ds_read_b128 v[170:173], v231 offset:51200
	ds_read_b128 v[186:189], v231 offset:52224
	ds_read_b128 v[166:169], v231 offset:53248
	ds_read_b128 v[182:185], v231 offset:54272
	ds_read_b128 v[162:165], v231 offset:55296
	ds_read_b128 v[178:181], v231 offset:56320

.LBB0_1612:
	s_mov_b32 m0, s54
	s_nop 0
	global_load_lds_dwordx4 v194, s[100:101]
	s_mov_b32 m0, s55
	s_nop 0
	global_load_lds_dwordx4 v196, s[100:101]
	v_add_u32_e32 v1, 0x10000, v232
	ds_read_b128 v[146:149], v1
	ds_read_b128 v[150:153], v1 offset:1024
	ds_read_b128 v[154:157], v1 offset:2048
	ds_read_b128 v[158:161], v1 offset:3072
	v_add_u32_e32 v1, 0x14000, v232
	ds_read_b128 v[130:133], v1
	ds_read_b128 v[134:137], v1 offset:1024
	ds_read_b128 v[138:141], v1 offset:2048
	ds_read_b128 v[142:145], v1 offset:3072
	v_lshl_add_u64 v[236:237], v[226:227], 0, s[48:49]
	s_add_i32 m0, s9, 0xc000
	s_waitcnt lgkmcnt(0)
	ds_read_b128 v[174:177], v233
	ds_read_b128 v[190:193], v233 offset:1024
	ds_read_b128 v[170:173], v233 offset:2048
	ds_read_b128 v[186:189], v233 offset:3072
	ds_read_b128 v[166:169], v233 offset:4096
	ds_read_b128 v[182:185], v233 offset:5120
	ds_read_b128 v[162:165], v233 offset:6144
	ds_read_b128 v[178:181], v233 offset:7168
	global_load_lds_dwordx4 v[236:237], off
	v_lshl_add_u64 v[236:237], v[228:229], 0, s[48:49]
	s_add_i32 m0, s9, 0xe000
	s_nop 0
	global_load_lds_dwordx4 v[236:237], off
	s_waitcnt vmcnt(8)
	s_waitcnt lgkmcnt(0)
	s_barrier
	s_setprio 0
	s_waitcnt lgkmcnt(0)
	v_mfma_f32_16x16x32_bf16 v[126:129], v[146:149], v[174:177], v[126:129]
	v_mfma_f32_16x16x32_bf16 v[122:125], v[154:157], v[174:177], v[122:125]
	v_mfma_f32_16x16x32_bf16 v[118:121], v[146:149], v[170:173], v[118:121]
	v_mfma_f32_16x16x32_bf16 v[110:113], v[154:157], v[170:173], v[110:113]
	v_mfma_f32_16x16x32_bf16 v[102:105], v[146:149], v[166:169], v[102:105]
	v_mfma_f32_16x16x32_bf16 v[94:97], v[154:157], v[166:169], v[94:97]
	v_mfma_f32_16x16x32_bf16 v[86:89], v[146:149], v[162:165], v[86:89]
	v_mfma_f32_16x16x32_bf16 v[78:81], v[154:157], v[162:165], v[78:81]
	v_mfma_f32_16x16x32_bf16 v[126:129], v[150:153], v[190:193], v[126:129]
	v_mfma_f32_16x16x32_bf16 v[122:125], v[158:161], v[190:193], v[122:125]
	v_mfma_f32_16x16x32_bf16 v[118:121], v[150:153], v[186:189], v[118:121]
	v_mfma_f32_16x16x32_bf16 v[110:113], v[158:161], v[186:189], v[110:113]
	v_mfma_f32_16x16x32_bf16 v[102:105], v[150:153], v[182:185], v[102:105]
	v_mfma_f32_16x16x32_bf16 v[94:97], v[158:161], v[182:185], v[94:97]
	v_mfma_f32_16x16x32_bf16 v[86:89], v[150:153], v[178:181], v[86:89]
	v_mfma_f32_16x16x32_bf16 v[78:81], v[158:161], v[178:181], v[78:81]
	s_setprio 1
	s_setprio 0
	v_mfma_f32_16x16x32_bf16 v[114:117], v[130:133], v[174:177], v[114:117]
	v_mfma_f32_16x16x32_bf16 v[106:109], v[138:141], v[174:177], v[106:109]
	v_mfma_f32_16x16x32_bf16 v[98:101], v[130:133], v[170:173], v[98:101]
	v_mfma_f32_16x16x32_bf16 v[90:93], v[138:141], v[170:173], v[90:93]
	v_mfma_f32_16x16x32_bf16 v[82:85], v[130:133], v[166:169], v[82:85]
	v_mfma_f32_16x16x32_bf16 v[74:77], v[138:141], v[166:169], v[74:77]
	v_mfma_f32_16x16x32_bf16 v[70:73], v[130:133], v[162:165], v[70:73]
	v_mfma_f32_16x16x32_bf16 v[66:69], v[138:141], v[162:165], v[66:69]
	v_mfma_f32_16x16x32_bf16 v[114:117], v[134:137], v[190:193], v[114:117]
	v_mfma_f32_16x16x32_bf16 v[106:109], v[142:145], v[190:193], v[106:109]
	v_mfma_f32_16x16x32_bf16 v[98:101], v[134:137], v[186:189], v[98:101]
	v_mfma_f32_16x16x32_bf16 v[90:93], v[142:145], v[186:189], v[90:93]
	s_barrier
	v_mfma_f32_16x16x32_bf16 v[82:85], v[134:137], v[182:185], v[82:85]
	v_mfma_f32_16x16x32_bf16 v[74:77], v[142:145], v[182:185], v[74:77]
	v_mfma_f32_16x16x32_bf16 v[70:73], v[134:137], v[178:181], v[70:73]
	v_mfma_f32_16x16x32_bf16 v[66:69], v[142:145], v[178:181], v[66:69]
	s_setprio 1
	v_cndmask_b32_e64 v1, 0, 1, s[40:41]
	v_cmp_ne_u32_e64 s[42:43], 1, v1
	s_andn2_b64 vcc, exec, s[40:41]
	s_cbranch_vccnz .LBB0_1614
	ds_read_b128 v[174:177], v233 offset:16384
	ds_read_b128 v[190:193], v233 offset:17408
	ds_read_b128 v[170:173], v233 offset:18432
	ds_read_b128 v[186:189], v233 offset:19456
	ds_read_b128 v[166:169], v233 offset:20480
	ds_read_b128 v[182:185], v233 offset:21504
	ds_read_b128 v[162:165], v233 offset:22528
	ds_read_b128 v[178:181], v233 offset:23552

.LBB0_1616:
	s_and_b64 vcc, s[38:39], s[56:57]
	v_cndmask_b32_e64 v131, v225, 0, vcc
	v_cndmask_b32_e32 v130, v224, v198, vcc
	v_lshl_add_u64 v[236:237], s[52:53], 0, v[130:131]
	s_barrier
	s_mov_b32 m0, s9
	s_nop 0
	global_load_lds_dwordx4 v194, s[98:99]
	s_mov_b32 m0, s14
	s_nop 0
	global_load_lds_dwordx4 v196, s[98:99]
	v_add_u32_e32 v1, 0x18000, v232
	ds_read_b128 v[146:149], v1
	ds_read_b128 v[150:153], v1 offset:1024
	ds_read_b128 v[154:157], v1 offset:2048
	ds_read_b128 v[158:161], v1 offset:3072
	v_add_u32_e32 v1, 0x1c000, v232
	ds_read_b128 v[130:133], v1
	ds_read_b128 v[134:137], v1 offset:1024
	ds_read_b128 v[138:141], v1 offset:2048
	ds_read_b128 v[142:145], v1 offset:3072
	s_mov_b32 m0, s15
	v_lshl_add_u64 v[238:239], v[236:237], 0, v[194:195]
	s_waitcnt lgkmcnt(0)
	ds_read_b128 v[174:177], v233 offset:32768
	ds_read_b128 v[190:193], v233 offset:33792
	ds_read_b128 v[170:173], v233 offset:34816
	ds_read_b128 v[186:189], v233 offset:35840
	ds_read_b128 v[166:169], v233 offset:36864
	ds_read_b128 v[182:185], v233 offset:37888
	ds_read_b128 v[162:165], v233 offset:38912
	ds_read_b128 v[178:181], v233 offset:39936
	global_load_lds_dwordx4 v[238:239], off
	v_lshl_add_u64 v[236:237], v[236:237], 0, v[196:197]
	s_mov_b32 m0, s16
	s_nop 0
	global_load_lds_dwordx4 v[236:237], off
	s_waitcnt vmcnt(8)
	s_waitcnt lgkmcnt(0)
	s_barrier
	s_setprio 0
	s_waitcnt lgkmcnt(0)
	v_mfma_f32_16x16x32_bf16 v[126:129], v[146:149], v[174:177], v[126:129]
	v_mfma_f32_16x16x32_bf16 v[122:125], v[154:157], v[174:177], v[122:125]
	v_mfma_f32_16x16x32_bf16 v[118:121], v[146:149], v[170:173], v[118:121]
	v_mfma_f32_16x16x32_bf16 v[110:113], v[154:157], v[170:173], v[110:113]
	v_mfma_f32_16x16x32_bf16 v[102:105], v[146:149], v[166:169], v[102:105]
	v_mfma_f32_16x16x32_bf16 v[94:97], v[154:157], v[166:169], v[94:97]
	v_mfma_f32_16x16x32_bf16 v[86:89], v[146:149], v[162:165], v[86:89]
	v_mfma_f32_16x16x32_bf16 v[78:81], v[154:157], v[162:165], v[78:81]
	v_mfma_f32_16x16x32_bf16 v[126:129], v[150:153], v[190:193], v[126:129]
	v_mfma_f32_16x16x32_bf16 v[122:125], v[158:161], v[190:193], v[122:125]
	v_mfma_f32_16x16x32_bf16 v[118:121], v[150:153], v[186:189], v[118:121]
	v_mfma_f32_16x16x32_bf16 v[110:113], v[158:161], v[186:189], v[110:113]
	v_mfma_f32_16x16x32_bf16 v[102:105], v[150:153], v[182:185], v[102:105]
	v_mfma_f32_16x16x32_bf16 v[94:97], v[158:161], v[182:185], v[94:97]
	v_mfma_f32_16x16x32_bf16 v[86:89], v[150:153], v[178:181], v[86:89]
	v_mfma_f32_16x16x32_bf16 v[78:81], v[158:161], v[178:181], v[78:81]
	s_setprio 1
	s_setprio 0
	v_mfma_f32_16x16x32_bf16 v[114:117], v[130:133], v[174:177], v[114:117]
	v_mfma_f32_16x16x32_bf16 v[106:109], v[138:141], v[174:177], v[106:109]
	v_mfma_f32_16x16x32_bf16 v[98:101], v[130:133], v[170:173], v[98:101]
	v_mfma_f32_16x16x32_bf16 v[90:93], v[138:141], v[170:173], v[90:93]
	v_mfma_f32_16x16x32_bf16 v[82:85], v[130:133], v[166:169], v[82:85]
	v_mfma_f32_16x16x32_bf16 v[74:77], v[138:141], v[166:169], v[74:77]
	v_mfma_f32_16x16x32_bf16 v[70:73], v[130:133], v[162:165], v[70:73]
	v_mfma_f32_16x16x32_bf16 v[66:69], v[138:141], v[162:165], v[66:69]
	v_mfma_f32_16x16x32_bf16 v[114:117], v[134:137], v[190:193], v[114:117]
	v_mfma_f32_16x16x32_bf16 v[106:109], v[142:145], v[190:193], v[106:109]
	v_mfma_f32_16x16x32_bf16 v[98:101], v[134:137], v[186:189], v[98:101]
	v_mfma_f32_16x16x32_bf16 v[90:93], v[142:145], v[186:189], v[90:93]
	s_barrier
	v_mfma_f32_16x16x32_bf16 v[82:85], v[134:137], v[182:185], v[82:85]
	v_mfma_f32_16x16x32_bf16 v[74:77], v[142:145], v[182:185], v[74:77]
	v_mfma_f32_16x16x32_bf16 v[70:73], v[134:137], v[178:181], v[70:73]
	v_mfma_f32_16x16x32_bf16 v[66:69], v[142:145], v[178:181], v[66:69]
	s_setprio 1
	s_and_b64 vcc, exec, s[42:43]
	s_cbranch_vccnz .LBB0_1618
	ds_read_b128 v[174:177], v233 offset:49152
	ds_read_b128 v[190:193], v233 offset:50176
	ds_read_b128 v[170:173], v233 offset:51200
	ds_read_b128 v[186:189], v233 offset:52224
	ds_read_b128 v[166:169], v233 offset:53248
	ds_read_b128 v[182:185], v233 offset:54272
	ds_read_b128 v[162:165], v233 offset:55296
	ds_read_b128 v[178:181], v233 offset:56320
